# tile scheduler in the G1/G5 tile loops: closed-form decode (pm = 8*(L&7) + ((L>>3)&7), pn = L>>6) instead of the generic remap with two integer divisions
# baseline (speedup 1.0000x reference)
.LBB0_128:
	s_add_i32 s55, s55, 1
	s_mul_i32 s6, s55, s47
	s_mul_hi_u32 s7, s55, s46
	s_add_i32 s7, s7, s6
	s_mul_i32 s6, s55, s46
	s_add_u32 s24, s6, s2
	s_addc_u32 s25, s7, s3
	v_mov_b64_e32 v[2:3], 0x380
	v_cmp_lt_i64_e64 s[6:7], s[24:25], v[2:3]
	v_mov_b64_e32 v[2:3], 0x37f
	v_cmp_gt_i64_e32 vcc, s[24:25], v[2:3]
	s_cbranch_vccnz .LBB0_130
	s_and_b32 s20, s24, 7
	s_lshl_b32 s20, s20, 3
	s_bfe_u32 s21, s24, 0x30003
	s_or_b32 s22, s20, s21
	s_lshr_b32 s20, s24, 6

.LBB0_854:
	s_add_i32 s70, s70, 1
	s_mul_i32 s4, s70, s47
	s_mul_hi_u32 s5, s70, s46
	s_add_i32 s5, s5, s4
	s_mul_i32 s4, s70, s46
	s_add_u32 s26, s4, s2
	s_addc_u32 s27, s5, s3
	v_cmp_gt_i64_e32 vcc, s[26:27], v[250:251]
	v_cmp_lt_i64_e64 s[8:9], s[26:27], v[248:249]
	s_cbranch_vccnz .LBB0_860
	s_and_b32 s4, s26, 7
	s_lshl_b32 s4, s4, 3
	s_bfe_u32 s5, s26, 0x30003
	s_or_b32 s24, s4, s5
	s_lshr_b32 s22, s26, 6
